# fused indexer/band/DSA phase rebalanced: CUs with heavy DSA units (j>=43) skip their band unit, CUs j<=20 run two band units
# speedup vs baseline: 1.0077x; 1.0021x over previous
; #define LAS __attribute__((address_space(3)))
; DEVI int otid() { int t = threadIdx.x; asm volatile("" : "+v"(t)); return t; }
; DEVI int crow(int r, int hi) { return (r & 3) + 8 * (r >> 2) + 4 * hi; }
; DEVI unsigned cvtpk(float lo, float hi) { unsigned r; asm volatile("v_cvt_pk_bf16_f32 %0, %1, %2" : "=v"(r) : "v"(lo), "v"(hi)); return r; }
; DEVI float xlane32(float v) { return __shfl_xor(v, 32); }
; template <int MODE>
; DEVI void attn_unit(LAS unsigned char* lds, const bf16_t* Qw, int ldq, const bf16_t* Kb, const bf16_t* Vb, int ldk, bf16_t* Ow, int ldo,
;                     int j_first, int ntiles, int jstep, int wj_lo, int wj_hi, int t0) {
;     ...
;     float rli[16];
;     if constexpr (MODE != M_STICK) {
;         l_reg += xlane32(l_reg);
;         if (hi == 0) li_l[r32] = l_reg; asm volatile("s_waitcnt lgkmcnt(0)" ::: "memory");
; #pragma unroll
;         for (int r = 0; r < 16; ++r) rli[r] = __builtin_amdgcn_rcpf(li_l[crow(r, hi)]);
;     } else {
; #pragma unroll
;         for (int r = 0; r < 16; ++r) rli[r] = 1.f;
;     }
; #pragma unroll
;     for (int r = 0; r < 16; ++r) { bf16_t* op = Ow + (size_t)crow(r, hi) * ldo + r32;
; #pragma unroll
;         for (int d0 = 0; d0 < 4; ++d0) { const float v = o[d0][r] * rli[r]; op[d0 * 32] = (bf16_t)cvtpk(v, v); } }
; DEVI void band_phase(LAS unsigned char* lds, const bf16_t* EV, bf16_t* O, const float* relb  ) {
;     const int wid = otid() >> 6;
;     for (int u = blockIdx.x; u < NB * 8 * 8; u += gridDim.x) {
;         const int qb = 7 - ((u >> 3) & 7), h = u & 7, b = u >> 6;
;         const int tw = qb * 256 + wid * 32, m0 = b * SEQ + tw, cw = tw >> 6;
;         { const int tb = otid(); if (tb < RELSZ) ((LAS float*)(lds + OFF_BIAS))[tb] = relb[h * RELSZ + tb] * 1.4426950408889634f; }
;         const int jlo = (4 * qb - 8) < 0 ? 0 : 4 * qb - 8, jhi = 4 * qb + 3;
;         attn_unit<M_BAND>(lds, EV + (size_t)m0 * EVP + EV_QB + h * HD, EVP, EV + (size_t)(b * SEQ) * EVP + EV_KB + h * HD, EV + (size_t)(b * SEQ) * EVP + EV_VB + h * HD, EVP,
;                           O + (size_t)m0 * DM + 1024 + h * HD, DM, jlo, jhi - jlo + 1, 1, cw - 8, cw, tw);
;     }
; }
.LBB11_1275:
	v_mov_b32_e32 v1, v0
	s_and_b64 vcc, exec, s[36:37]
	s_cbranch_vccnz .LBB11_1301
	v_readlane_b32 s1, v252, 16
	s_and_b32 s1, s1, 8
	v_readlane_b32 s12, v249, 17
	s_mulk_i32 s1, 0x300
	v_readlane_b32 s18, v249, 23
	v_ashrrev_i32_e32 v1, 1, v1
	v_readlane_b32 s19, v249, 24
	s_add_u32 s10, s18, s1
	v_and_b32_e32 v1, 0xffffffe0, v1
	s_addc_u32 s11, s19, 0
	v_add_u32_e32 v183, 36, v1
	v_readlane_b32 s1, v255, 8
	s_and_b32 s101, s1, 63
	s_cmp_ge_u32 s101, 43
	s_cbranch_scc1 .LBB11_1301
	s_cmp_le_u32 s101, 20
	s_cselect_b32 s101, 43, 0x100
	v_readlane_b32 s13, v249, 18
	v_readlane_b32 s14, v249, 19
	v_readlane_b32 s15, v249, 20
	v_readlane_b32 s16, v249, 21
	v_readlane_b32 s17, v249, 22
	v_readlane_b32 s20, v249, 25
	v_readlane_b32 s21, v249, 26
	v_readlane_b32 s22, v249, 27
	v_readlane_b32 s23, v249, 28
	v_readlane_b32 s24, v249, 29
	v_readlane_b32 s25, v249, 30
	v_readlane_b32 s26, v249, 31
	v_readlane_b32 s27, v249, 32
	s_branch .LBB11_1278
.LBB11_1277:
	s_or_b64 exec, exec, s[4:5]
	s_waitcnt lgkmcnt(0)
	s_waitcnt lgkmcnt(0)
	v_lshl_add_u32 v2, v221, 4, v222
	ds_read_b128 v[68:71], v2
	v_lshlrev_b64 v[72:73], 12, v[198:199]
	v_lshl_add_u64 v[72:73], s[2:3], 0, v[72:73]
	s_lshl_b32 s30, s14, 1
	v_lshl_add_u64 v[76:77], v[72:73], 0, s[30:31]
	ds_read_b128 v[72:75], v2 offset:32
	s_waitcnt lgkmcnt(0)
	v_rcp_f32_e32 v78, v68
	v_rcp_f32_e32 v79, v69
	v_rcp_f32_e32 v80, v70
	v_rcp_f32_e32 v81, v71
	ds_read_b128 v[68:71], v2 offset:64
	v_rcp_f32_e32 v82, v72
	v_rcp_f32_e32 v83, v73
	v_rcp_f32_e32 v84, v74
	v_rcp_f32_e32 v85, v75
	ds_read_b128 v[72:75], v2 offset:96
	v_lshlrev_b32_e32 v2, 1, v220
	s_waitcnt lgkmcnt(0)
	v_rcp_f32_e32 v86, v68
	v_rcp_f32_e32 v87, v69
	v_rcp_f32_e32 v88, v70
	v_rcp_f32_e32 v89, v71
	v_lshlrev_b32_e32 v68, 14, v221
	v_lshl_add_u64 v[70:71], v[76:77], 0, v[2:3]
	v_mov_b32_e32 v69, v3
	v_lshl_add_u64 v[68:69], v[70:71], 0, v[68:69]
	s_mov_b64 s[4:5], 0x59200800
	v_lshl_add_u64 v[70:71], v[68:69], 0, s[4:5]
	s_mov_b32 s4, 0x59200000
	v_rcp_f32_e32 v90, v72
	v_mul_f32_e32 v2, v52, v78
	v_add_co_u32_e32 v72, vcc, s4, v68
	v_rcp_f32_e32 v91, v73
	v_cvt_pk_bf16_f32 v2, v2, v2
	s_nop 0
	v_addc_co_u32_e32 v73, vcc, 0, v69, vcc
	global_store_short v[72:73], v2, off offset:2048
	v_mul_f32_e32 v2, v36, v78
	v_cvt_pk_bf16_f32 v2, v2, v2
	global_store_short v[70:71], v2, off offset:64
	v_mul_f32_e32 v2, v20, v78
	v_cvt_pk_bf16_f32 v2, v2, v2
	global_store_short v[70:71], v2, off offset:128
	v_mul_f32_e32 v2, v4, v78
	v_cvt_pk_bf16_f32 v2, v2, v2
	s_mov_b32 s4, 0x59201000
	global_store_short v[70:71], v2, off offset:192
	v_mul_f32_e32 v2, v53, v79
	v_add_co_u32_e32 v52, vcc, s4, v68
	v_cvt_pk_bf16_f32 v2, v2, v2
	s_mov_b32 s4, 0x59202000
	s_nop 0
	v_addc_co_u32_e32 v53, vcc, 0, v69, vcc
	global_store_short v[52:53], v2, off offset:2048
	v_mul_f32_e32 v2, v37, v79
	v_cvt_pk_bf16_f32 v2, v2, v2
	global_store_short v[52:53], v2, off offset:2112
	v_mul_f32_e32 v2, v21, v79
	v_cvt_pk_bf16_f32 v2, v2, v2
	global_store_short v[52:53], v2, off offset:2176
	v_mul_f32_e32 v2, v5, v79
	v_cvt_pk_bf16_f32 v2, v2, v2
	global_store_short v[52:53], v2, off offset:2240
	v_mul_f32_e32 v2, v54, v80
	v_add_co_u32_e32 v4, vcc, s4, v68
	v_cvt_pk_bf16_f32 v2, v2, v2
	s_mov_b32 s4, 0x59203000
	s_nop 0
	v_addc_co_u32_e32 v5, vcc, 0, v69, vcc
	global_store_short v[4:5], v2, off offset:2048
	v_mul_f32_e32 v2, v38, v80
	v_cvt_pk_bf16_f32 v2, v2, v2
	global_store_short v[4:5], v2, off offset:2112
	v_mul_f32_e32 v2, v22, v80
	v_cvt_pk_bf16_f32 v2, v2, v2
	global_store_short v[4:5], v2, off offset:2176
	v_mul_f32_e32 v2, v6, v80
	v_cvt_pk_bf16_f32 v2, v2, v2
	global_store_short v[4:5], v2, off offset:2240
	v_mul_f32_e32 v2, v55, v81
	v_add_co_u32_e32 v4, vcc, s4, v68
	v_cvt_pk_bf16_f32 v2, v2, v2
	s_mov_b32 s4, 0x59208000
	s_nop 0
	v_addc_co_u32_e32 v5, vcc, 0, v69, vcc
	global_store_short v[4:5], v2, off offset:2048
	v_mul_f32_e32 v2, v39, v81
	v_cvt_pk_bf16_f32 v2, v2, v2
	global_store_short v[4:5], v2, off offset:2112
	v_mul_f32_e32 v2, v23, v81
	v_cvt_pk_bf16_f32 v2, v2, v2
	global_store_short v[4:5], v2, off offset:2176
	v_mul_f32_e32 v2, v7, v81
	v_cvt_pk_bf16_f32 v2, v2, v2
	global_store_short v[4:5], v2, off offset:2240
	v_mul_f32_e32 v2, v56, v82
	v_add_co_u32_e32 v4, vcc, s4, v68
	v_cvt_pk_bf16_f32 v2, v2, v2
	s_mov_b32 s4, 0x59209000
	s_nop 0
	v_addc_co_u32_e32 v5, vcc, 0, v69, vcc
	global_store_short v[4:5], v2, off offset:2048
	v_mul_f32_e32 v2, v40, v82
	v_cvt_pk_bf16_f32 v2, v2, v2
	global_store_short v[4:5], v2, off offset:2112
	v_mul_f32_e32 v2, v24, v82
	v_cvt_pk_bf16_f32 v2, v2, v2
	global_store_short v[4:5], v2, off offset:2176
	v_mul_f32_e32 v2, v8, v82
	v_cvt_pk_bf16_f32 v2, v2, v2
	global_store_short v[4:5], v2, off offset:2240
	v_mul_f32_e32 v2, v57, v83
	v_add_co_u32_e32 v4, vcc, s4, v68
	v_cvt_pk_bf16_f32 v2, v2, v2
	s_mov_b32 s4, 0x5920a000
	s_nop 0
	v_addc_co_u32_e32 v5, vcc, 0, v69, vcc
	global_store_short v[4:5], v2, off offset:2048
	v_mul_f32_e32 v2, v41, v83
	v_cvt_pk_bf16_f32 v2, v2, v2
	global_store_short v[4:5], v2, off offset:2112
	v_mul_f32_e32 v2, v25, v83
	v_cvt_pk_bf16_f32 v2, v2, v2
	global_store_short v[4:5], v2, off offset:2176
	v_mul_f32_e32 v2, v9, v83
	v_cvt_pk_bf16_f32 v2, v2, v2
	global_store_short v[4:5], v2, off offset:2240
	v_mul_f32_e32 v2, v58, v84
	v_add_co_u32_e32 v4, vcc, s4, v68
	v_cvt_pk_bf16_f32 v2, v2, v2
	s_mov_b32 s4, 0x5920b000
	s_nop 0
; #define LAS __attribute__((address_space(3)))
; DEVI int otid() { int t = threadIdx.x; asm volatile("" : "+v"(t)); return t; }
; DEVI int crow(int r, int hi) { return (r & 3) + 8 * (r >> 2) + 4 * hi; }
; DEVI unsigned cvtpk(float lo, float hi) { unsigned r; asm volatile("v_cvt_pk_bf16_f32 %0, %1, %2" : "=v"(r) : "v"(lo), "v"(hi)); return r; }
; template <int MODE>
; DEVI void attn_unit(LAS unsigned char* lds, const bf16_t* Qw, int ldq, const bf16_t* Kb, const bf16_t* Vb, int ldk, bf16_t* Ow, int ldo,
;                     int j_first, int ntiles, int jstep, int wj_lo, int wj_hi, int t0) {
;     ...
;     for (int r = 0; r < 16; ++r) { bf16_t* op = Ow + (size_t)crow(r, hi) * ldo + r32;
; #pragma unroll
;         for (int d0 = 0; d0 < 4; ++d0) { const float v = o[d0][r] * rli[r]; op[d0 * 32] = (bf16_t)cvtpk(v, v); } }
;     __builtin_amdgcn_s_setprio(0);
;     asm volatile("s_waitcnt lgkmcnt(0)" ::: "memory"); __builtin_amdgcn_s_barrier(); asm volatile("" ::: "memory");
; DEVI void band_phase(LAS unsigned char* lds, const bf16_t* EV, bf16_t* O, const float* relb  ) {
;     ...
;     for (int u = blockIdx.x; u < NB * 8 * 8; u += gridDim.x) {
;         const int qb = 7 - ((u >> 3) & 7), h = u & 7, b = u >> 6;
;         const int tw = qb * 256 + wid * 32, m0 = b * SEQ + tw, cw = tw >> 6;
;         { const int tb = otid(); if (tb < RELSZ) ((LAS float*)(lds + OFF_BIAS))[tb] = relb[h * RELSZ + tb] * 1.4426950408889634f; }
;         const int jlo = (4 * qb - 8) < 0 ? 0 : 4 * qb - 8, jhi = 4 * qb + 3;
;         attn_unit<M_BAND>(lds, EV + (size_t)m0 * EVP + EV_QB + h * HD, EVP, EV + (size_t)(b * SEQ) * EVP + EV_KB + h * HD, EV + (size_t)(b * SEQ) * EVP + EV_VB + h * HD, EVP,
;                           O + (size_t)m0 * DM + 1024 + h * HD, DM, jlo, jhi - jlo + 1, 1, cw - 8, cw, tw);
	v_addc_co_u32_e32 v5, vcc, 0, v69, vcc
	global_store_short v[4:5], v2, off offset:2048
	v_mul_f32_e32 v2, v42, v84
	v_cvt_pk_bf16_f32 v2, v2, v2
	global_store_short v[4:5], v2, off offset:2112
	v_mul_f32_e32 v2, v26, v84
	v_cvt_pk_bf16_f32 v2, v2, v2
	global_store_short v[4:5], v2, off offset:2176
	v_mul_f32_e32 v2, v10, v84
	v_cvt_pk_bf16_f32 v2, v2, v2
	global_store_short v[4:5], v2, off offset:2240
	v_mul_f32_e32 v2, v59, v85
	v_add_co_u32_e32 v4, vcc, s4, v68
	v_cvt_pk_bf16_f32 v2, v2, v2
	s_mov_b32 s4, 0x59210000
	s_nop 0
	v_addc_co_u32_e32 v5, vcc, 0, v69, vcc
	global_store_short v[4:5], v2, off offset:2048
	v_mul_f32_e32 v2, v43, v85
	v_cvt_pk_bf16_f32 v2, v2, v2
	global_store_short v[4:5], v2, off offset:2112
	v_mul_f32_e32 v2, v27, v85
	v_cvt_pk_bf16_f32 v2, v2, v2
	global_store_short v[4:5], v2, off offset:2176
	v_mul_f32_e32 v2, v11, v85
	v_cvt_pk_bf16_f32 v2, v2, v2
	global_store_short v[4:5], v2, off offset:2240
	v_mul_f32_e32 v2, v60, v86
	v_add_co_u32_e32 v4, vcc, s4, v68
	v_cvt_pk_bf16_f32 v2, v2, v2
	s_mov_b32 s4, 0x59211000
	s_nop 0
	v_addc_co_u32_e32 v5, vcc, 0, v69, vcc
	global_store_short v[4:5], v2, off offset:2048
	v_mul_f32_e32 v2, v44, v86
	v_cvt_pk_bf16_f32 v2, v2, v2
	global_store_short v[4:5], v2, off offset:2112
	v_mul_f32_e32 v2, v28, v86
	v_cvt_pk_bf16_f32 v2, v2, v2
	global_store_short v[4:5], v2, off offset:2176
	v_mul_f32_e32 v2, v12, v86
	v_cvt_pk_bf16_f32 v2, v2, v2
	global_store_short v[4:5], v2, off offset:2240
	v_mul_f32_e32 v2, v61, v87
	v_add_co_u32_e32 v4, vcc, s4, v68
	v_cvt_pk_bf16_f32 v2, v2, v2
	s_mov_b32 s4, 0x59212000
	s_nop 0
	v_addc_co_u32_e32 v5, vcc, 0, v69, vcc
	global_store_short v[4:5], v2, off offset:2048
	v_mul_f32_e32 v2, v45, v87
	v_cvt_pk_bf16_f32 v2, v2, v2
	global_store_short v[4:5], v2, off offset:2112
	v_mul_f32_e32 v2, v29, v87
	v_cvt_pk_bf16_f32 v2, v2, v2
	global_store_short v[4:5], v2, off offset:2176
	v_mul_f32_e32 v2, v13, v87
	v_cvt_pk_bf16_f32 v2, v2, v2
	global_store_short v[4:5], v2, off offset:2240
	v_mul_f32_e32 v2, v62, v88
	v_add_co_u32_e32 v4, vcc, s4, v68
	v_cvt_pk_bf16_f32 v2, v2, v2
	s_mov_b32 s4, 0x59213000
	s_nop 0
	v_addc_co_u32_e32 v5, vcc, 0, v69, vcc
	global_store_short v[4:5], v2, off offset:2048
	v_mul_f32_e32 v2, v46, v88
	v_cvt_pk_bf16_f32 v2, v2, v2
	global_store_short v[4:5], v2, off offset:2112
	v_mul_f32_e32 v2, v30, v88
	v_cvt_pk_bf16_f32 v2, v2, v2
	global_store_short v[4:5], v2, off offset:2176
	v_mul_f32_e32 v2, v14, v88
	v_cvt_pk_bf16_f32 v2, v2, v2
	global_store_short v[4:5], v2, off offset:2240
	v_mul_f32_e32 v2, v63, v89
	v_add_co_u32_e32 v4, vcc, s4, v68
	v_cvt_pk_bf16_f32 v2, v2, v2
	s_mov_b32 s4, 0x59218000
	s_nop 0
	v_addc_co_u32_e32 v5, vcc, 0, v69, vcc
	global_store_short v[4:5], v2, off offset:2048
	v_mul_f32_e32 v2, v47, v89
	v_cvt_pk_bf16_f32 v2, v2, v2
	global_store_short v[4:5], v2, off offset:2112
	v_mul_f32_e32 v2, v31, v89
	v_cvt_pk_bf16_f32 v2, v2, v2
	global_store_short v[4:5], v2, off offset:2176
	v_mul_f32_e32 v2, v15, v89
	v_cvt_pk_bf16_f32 v2, v2, v2
	global_store_short v[4:5], v2, off offset:2240
	v_mul_f32_e32 v2, v64, v90
	v_add_co_u32_e32 v4, vcc, s4, v68
	v_cvt_pk_bf16_f32 v2, v2, v2
	s_mov_b32 s4, 0x59219000
	s_nop 0
	v_addc_co_u32_e32 v5, vcc, 0, v69, vcc
	global_store_short v[4:5], v2, off offset:2048
	v_mul_f32_e32 v2, v48, v90
	v_cvt_pk_bf16_f32 v2, v2, v2
	global_store_short v[4:5], v2, off offset:2112
	v_mul_f32_e32 v2, v32, v90
	v_cvt_pk_bf16_f32 v2, v2, v2
	global_store_short v[4:5], v2, off offset:2176
	v_mul_f32_e32 v2, v16, v90
	v_cvt_pk_bf16_f32 v2, v2, v2
	global_store_short v[4:5], v2, off offset:2240
	v_mul_f32_e32 v2, v65, v91
	v_add_co_u32_e32 v4, vcc, s4, v68
	v_cvt_pk_bf16_f32 v2, v2, v2
	v_rcp_f32_e32 v74, v74
	s_nop 0
	v_addc_co_u32_e32 v5, vcc, 0, v69, vcc
	global_store_short v[4:5], v2, off offset:2048
	v_mul_f32_e32 v2, v49, v91
	v_cvt_pk_bf16_f32 v2, v2, v2
	global_store_short v[4:5], v2, off offset:2112
	v_mul_f32_e32 v2, v33, v91
	v_cvt_pk_bf16_f32 v2, v2, v2
	global_store_short v[4:5], v2, off offset:2176
	v_mul_f32_e32 v2, v17, v91
	v_cvt_pk_bf16_f32 v2, v2, v2
	s_mov_b32 s4, 0x5921a000
	global_store_short v[4:5], v2, off offset:2240
	v_mul_f32_e32 v2, v66, v74
	v_add_co_u32_e32 v4, vcc, s4, v68
	v_cvt_pk_bf16_f32 v2, v2, v2
	v_rcp_f32_e32 v75, v75
	s_nop 0
	v_addc_co_u32_e32 v5, vcc, 0, v69, vcc
	global_store_short v[4:5], v2, off offset:2048
	v_mul_f32_e32 v2, v50, v74
	v_cvt_pk_bf16_f32 v2, v2, v2
	global_store_short v[4:5], v2, off offset:2112
	v_mul_f32_e32 v2, v34, v74
	v_cvt_pk_bf16_f32 v2, v2, v2
	global_store_short v[4:5], v2, off offset:2176
	v_mul_f32_e32 v2, v18, v74
	v_cvt_pk_bf16_f32 v2, v2, v2
	s_mov_b32 s4, 0x5921b000
	global_store_short v[4:5], v2, off offset:2240
	v_mul_f32_e32 v2, v67, v75
	v_add_co_u32_e32 v4, vcc, s4, v68
	v_cvt_pk_bf16_f32 v2, v2, v2
	s_nop 1
	v_addc_co_u32_e32 v5, vcc, 0, v69, vcc
	global_store_short v[4:5], v2, off offset:2048
	v_mul_f32_e32 v2, v51, v75
	v_cvt_pk_bf16_f32 v2, v2, v2
	global_store_short v[4:5], v2, off offset:2112
	v_mul_f32_e32 v2, v35, v75
	v_cvt_pk_bf16_f32 v2, v2, v2
	global_store_short v[4:5], v2, off offset:2176
	v_mul_f32_e32 v2, v19, v75
	v_cvt_pk_bf16_f32 v2, v2, v2
	global_store_short v[4:5], v2, off offset:2240
	s_setprio 0
	s_waitcnt lgkmcnt(0)
	s_barrier
	v_readlane_b32 s4, v249, 37
	s_add_i32 s1, s1, s101
	s_movk_i32 s101, 0x100
	s_cmpk_lt_i32 s1, 0x100
	s_cbranch_scc0 .LBB11_1301
